# speedup vs baseline: 1.0053x; 1.0001x over previous
; #define SBAR() __builtin_amdgcn_sched_barrier(0)
; #define SLOAD(i, t) do { const long rb_ = TROW(t); const char* vt_ = (const char*)Vh + rb_ * (LDK * 2); const char* kt_ = (const char*)Kh + rb_ * (LDK * 2); \
;     sr_[i].vs0 = *(const bf16x8*)(vt_ + lo0); sr_[i].vs1 = *(const bf16x8*)(vt_ + lo0 + 32 * LDK * 2); \
;     sr_[i].ks0 = *(const bf16x8*)(kt_ + lo0); sr_[i].ks1 = *(const bf16x8*)(kt_ + lo0 + 32 * LDK * 2); } while (0)
; __device__ __forceinline__ void finishSM(f32x16& p0, f32x16& p1, float alpha, float& l_reg, bf16x8& pa0, bf16x8& pa1, bf16x8& pa2, bf16x8& pa3) {
; #pragma unroll
;   for (int r = 0; r < 16; ++r) p1[r] = __builtin_amdgcn_exp2f(p1[r]);
;   float ps = 0;
; #pragma unroll
;   for (int r = 0; r < 16; ++r) ps += p0[r];
; #pragma unroll
;   for (int r = 0; r < 16; ++r) ps += p1[r];
;   { auto rr = __builtin_amdgcn_permlane32_swap(__float_as_uint(ps), __float_as_uint(ps), false, false);
;     ps = __uint_as_float(rr[0]) + __uint_as_float(rr[1]); }
;   l_reg = l_reg * alpha + ps;
;     ...
;   PK4(p0, 0, pa0); PK4(p0, 8, pa1); PK4(p1, 0, pa2); PK4(p1, 8, pa3);
;     ...
; }
; __device__ __forceinline__ void qkt(f32x16& p0, f32x16& p1, const bf16_t* Ks, const bf16x8* qr, int r32, int hi) {
;   p0 = f32x16{}; p1 = f32x16{};
; #pragma unroll
;   for (int d0 = 0; d0 < 8; ++d0) { int cb = (d0 * 16 + hi * 8) * 2;
;     bf16x8 b0 = *reinterpret_cast<const bf16x8*>((const char*)Ks + KSWZ(r32, cb));
;     bf16x8 b1 = *reinterpret_cast<const bf16x8*>((const char*)Ks + KSWZ(32 + r32, cb));
;     p0 = __builtin_amdgcn_mfma_f32_32x32x16_bf16(b0, qr[d0], p0, 0, 0, 0);
;     p1 = __builtin_amdgcn_mfma_f32_32x32x16_bf16(b1, qr[d0], p1, 0, 0, 0); }
; }
; template <bool META>
; __device__ __forceinline__ void attn_unit(const bf16_t* Q, bf16_t* Oo, const bf16_t* __restrict__ Kb, const bf16_t* __restrict__ Vb, int b, int kvh, int h, int qb, char* lds, const int tid, const float* qn, const float* RT) {
;     ...
;   for (int j = 1; j + 1 < NT; j += 2) {
;     const int bn = bc == 2 ? 0 : bc + 1, bp = bc == 0 ? 2 : bc - 1;
;     SBAR(); qkt(pB0, pB1, (bf16_t*)((char*)K_lds + bc * SHM_K), qr, r32, hi);
;     finishSM(pA0, pA1, alA, l_reg, pa0, pa1, pa2, pa3); SBAR();
;     SLOAD(SO, j + 1);
.LBB0_260:
	s_mov_b32 s6, s28
	v_sub_co_u32_e64 v66, s[0:1], s6, 1
	s_and_b64 s[0:1], s[0:1], exec
	v_readfirstlane_b32 s0, v66
	s_cselect_b32 s28, 2, s0
	s_lshl_b32 s9, s6, 14
	s_add_i32 s0, s9, 0
	v_add_u32_e32 v195, s0, v182
	ds_read_b128 v[66:69], v195 offset:49152
	ds_read_b128 v[70:73], v195 offset:50176
	ds_read_b128 v[210:213], v195 offset:51200
	ds_read_b128 v[214:217], v195 offset:52224
	s_waitcnt lgkmcnt(3)
	s_setprio 1
	v_mfma_f32_32x32x16_bf16 v[82:97], v[66:69], v[98:101], 0
	v_exp_f32_e32 v144, v144
	v_exp_f32_e32 v145, v145
	v_exp_f32_e32 v142, v142
	v_exp_f32_e32 v143, v143
	v_exp_f32_e32 v140, v140
	v_exp_f32_e32 v141, v141
	v_exp_f32_e32 v138, v138
	s_waitcnt lgkmcnt(2)
	v_mfma_f32_32x32x16_bf16 v[66:81], v[70:73], v[98:101], 0
	v_exp_f32_e32 v139, v139
	v_exp_f32_e32 v136, v136
	v_exp_f32_e32 v137, v137
	v_exp_f32_e32 v134, v134
	v_exp_f32_e32 v135, v135
	v_exp_f32_e32 v132, v132
	v_exp_f32_e32 v133, v133
	s_waitcnt lgkmcnt(1)
	v_mfma_f32_32x32x16_bf16 v[82:97], v[210:213], v[102:105], v[82:97]
	v_exp_f32_e32 v130, v130
	v_exp_f32_e32 v131, v131
	s_waitcnt lgkmcnt(0)
	v_mfma_f32_32x32x16_bf16 v[66:81], v[214:217], v[102:105], v[66:81]
	ds_read_b128 v[210:213], v195 offset:53248
	ds_read_b128 v[214:217], v195 offset:54272
	s_waitcnt lgkmcnt(1)
	v_mfma_f32_32x32x16_bf16 v[82:97], v[210:213], v[106:109], v[82:97]
	s_waitcnt lgkmcnt(0)
	v_mfma_f32_32x32x16_bf16 v[66:81], v[214:217], v[106:109], v[66:81]
	ds_read_b128 v[210:213], v195 offset:55296
	ds_read_b128 v[214:217], v195 offset:56320
	s_waitcnt lgkmcnt(1)
	v_mfma_f32_32x32x16_bf16 v[82:97], v[210:213], v[110:113], v[82:97]
	s_waitcnt lgkmcnt(0)
	v_mfma_f32_32x32x16_bf16 v[66:81], v[214:217], v[110:113], v[66:81]
	ds_read_b128 v[210:213], v195 offset:57344
	ds_read_b128 v[214:217], v195 offset:58368
	s_waitcnt lgkmcnt(1)
	v_mfma_f32_32x32x16_bf16 v[82:97], v[210:213], v[114:117], v[82:97]
	s_waitcnt lgkmcnt(0)
	v_mfma_f32_32x32x16_bf16 v[66:81], v[214:217], v[114:117], v[66:81]
	ds_read_b128 v[210:213], v195 offset:59392
	ds_read_b128 v[214:217], v195 offset:60416
	s_waitcnt lgkmcnt(1)
	v_mfma_f32_32x32x16_bf16 v[82:97], v[210:213], v[118:121], v[82:97]
	s_waitcnt lgkmcnt(0)
	v_mfma_f32_32x32x16_bf16 v[66:81], v[214:217], v[118:121], v[66:81]
	ds_read_b128 v[210:213], v195 offset:61440
	ds_read_b128 v[214:217], v195 offset:62464
	s_waitcnt lgkmcnt(1)
	v_mfma_f32_32x32x16_bf16 v[82:97], v[210:213], v[122:125], v[82:97]
	s_waitcnt lgkmcnt(0)
	v_mfma_f32_32x32x16_bf16 v[66:81], v[214:217], v[122:125], v[66:81]
	ds_read_b128 v[210:213], v195 offset:63488
	ds_read_b128 v[214:217], v195 offset:64512
	v_add_f32_e32 v193, v147, v146
	v_add_f32_e32 v193, v148, v193
	v_add_f32_e32 v193, v159, v193
	v_add_f32_e32 v193, v160, v193
	v_add_f32_e32 v193, v209, v193
	v_add_f32_e32 v193, v149, v193
	v_add_f32_e32 v193, v161, v193
	v_add_f32_e32 v193, v151, v193
	v_add_f32_e32 v193, v153, v193
	v_add_f32_e32 v193, v154, v193
	v_add_f32_e32 v193, v157, v193
	v_add_f32_e32 v193, v152, v193
	v_add_f32_e32 v193, v155, v193
	v_add_f32_e32 v193, v156, v193
	v_add_f32_e32 v193, v158, v193
	v_add_f32_e32 v193, v144, v193
	v_add_f32_e32 v193, v145, v193
	v_add_f32_e32 v193, v142, v193
	v_add_f32_e32 v193, v143, v193
	v_add_f32_e32 v193, v140, v193
	v_add_f32_e32 v193, v141, v193
	v_add_f32_e32 v193, v138, v193
	v_add_f32_e32 v193, v139, v193
	v_add_f32_e32 v193, v136, v193
	v_add_f32_e32 v193, v137, v193
	s_waitcnt lgkmcnt(1)
	v_mfma_f32_32x32x16_bf16 v[82:97], v[210:213], v[126:129], v[82:97]
	v_add_f32_e32 v193, v134, v193
	v_add_f32_e32 v193, v135, v193
	v_add_f32_e32 v193, v132, v193
	v_add_f32_e32 v193, v133, v193
	v_add_f32_e32 v193, v130, v193
	v_add_f32_e32 v193, v131, v193
	v_mov_b32_e32 v195, v193
	s_waitcnt lgkmcnt(0)
	v_mfma_f32_32x32x16_bf16 v[66:81], v[214:217], v[126:129], v[66:81]
	s_setprio 0
	v_cvt_pk_bf16_f32 v146, v146, v147
	v_cvt_pk_bf16_f32 v147, v148, v159
	v_cvt_pk_bf16_f32 v148, v160, v209
	v_permlane32_swap_b32_e32 v193, v195
	v_cvt_pk_bf16_f32 v149, v149, v161
	v_permlane32_swap_b32_e32 v146, v148
	v_cvt_pk_bf16_f32 v210, v151, v153
	v_cvt_pk_bf16_f32 v211, v154, v157
	v_cvt_pk_bf16_f32 v212, v152, v155
	v_cvt_pk_bf16_f32 v213, v156, v158
	v_cvt_pk_bf16_f32 v152, v144, v145
	v_cvt_pk_bf16_f32 v153, v142, v143
	v_cvt_pk_bf16_f32 v154, v140, v141
	v_cvt_pk_bf16_f32 v155, v138, v139
	v_cvt_pk_bf16_f32 v156, v136, v137
	v_cvt_pk_bf16_f32 v157, v134, v135
	v_cvt_pk_bf16_f32 v158, v132, v133
	v_cvt_pk_bf16_f32 v159, v130, v131
	v_permlane32_swap_b32_e32 v147, v149
	v_permlane32_swap_b32_e32 v210, v212
	v_permlane32_swap_b32_e32 v211, v213
	v_permlane32_swap_b32_e32 v152, v154
	v_permlane32_swap_b32_e32 v153, v155
	v_permlane32_swap_b32_e32 v156, v158
	v_permlane32_swap_b32_e32 v157, v159
	s_lshl_b32 s8, s28, 14
	v_add_u32_e32 v151, s8, v178
	ds_read_b64_tr_b16 v[214:215], v151 offset:0
	ds_read_b64_tr_b16 v[216:217], v151 offset:0x800
	ds_read_b64_tr_b16 v[218:219], v151 offset:0x1000
	ds_read_b64_tr_b16 v[220:221], v151 offset:0x1800
	ds_read_b64_tr_b16 v[222:223], v151 offset:0x2000
	ds_read_b64_tr_b16 v[224:225], v151 offset:0x2800
	ds_read_b64_tr_b16 v[226:227], v151 offset:0x3000
	ds_read_b64_tr_b16 v[228:229], v151 offset:0x3800
	s_cmpk_lg_i32 s4, 0xfd
	s_cselect_b64 s[0:1], -1, 0
	s_cmpk_eq_i32 s4, 0xfd
	s_cselect_b64 s[40:41], -1, 0
	s_and_b64 s[10:11], s[40:41], exec
	s_cselect_b32 s11, s44, s91
	s_cselect_b32 s10, s31, s90
	s_lshl_b64 s[10:11], s[10:11], 9
	s_setprio 1
	s_add_i32 s19, s9, 0x4000
	s_cmp_lg_u32 s6, 2
	s_cselect_b32 s19, s19, 0
	s_add_i32 s19, s19, s18
	s_add_u32 s16, s12, s10
	s_addc_u32 s17, s13, s11
	s_mov_b32 m0, s19
	s_nop 0
	global_load_lds_dwordx4 v187, s[16:17]
	s_add_i32 m0, s19, 0x380
	s_nop 0
	global_load_lds_dwordx4 v187, s[16:17] offset:128
	s_add_u32 s16, s14, s10
	s_addc_u32 s17, s15, s11
	s_add_i32 m0, s19, 0xc000
	s_nop 0
	global_load_lds_dwordx4 v188, s[16:17]
	s_add_u32 s16, s16, 0x4000
	s_addc_u32 s17, s17, 0
	s_add_i32 m0, s19, 0xc400
	s_nop 0
	global_load_lds_dwordx4 v188, s[16:17]
	s_waitcnt lgkmcnt(6)
; #define SBAR() __builtin_amdgcn_sched_barrier(0)
; template <int D0> __device__ __forceinline__ void pv_one(f32x16& od, int vb, bf16x8 pa0, bf16x8 pa1, bf16x8 pa2, bf16x8 pa3) {
;   const s16x4 l0 = tr_read<v_rd_off(D0, 0, 0)>(vb), h0 = tr_read<v_rd_off(D0, 0, 1)>(vb), l1 = tr_read<v_rd_off(D0, 1, 0)>(vb), h1 = tr_read<v_rd_off(D0, 1, 1)>(vb);
;   const s16x4 l2 = tr_read<v_rd_off(D0, 2, 0)>(vb), h2 = tr_read<v_rd_off(D0, 2, 1)>(vb), l3 = tr_read<v_rd_off(D0, 3, 0)>(vb), h3 = tr_read<v_rd_off(D0, 3, 1)>(vb);
;   asm volatile("s_waitcnt lgkmcnt(0)" ::: "memory"); SBAR();
;     ...
;   od = __builtin_amdgcn_mfma_f32_32x32x16_bf16(pa0, PK(l0, h0), od, 0, 0, 0);
;   od = __builtin_amdgcn_mfma_f32_32x32x16_bf16(pa1, PK(l1, h1), od, 0, 0, 0);
;   od = __builtin_amdgcn_mfma_f32_32x32x16_bf16(pa2, PK(l2, h2), od, 0, 0, 0);
;   od = __builtin_amdgcn_mfma_f32_32x32x16_bf16(pa3, PK(l3, h3), od, 0, 0, 0);
;     ...
; }
; __device__ __forceinline__ void pv_d0(f32x16* o, int vb, bf16x8 pa0, bf16x8 pa1, bf16x8 pa2, bf16x8 pa3) {
;   pv_one<0>(o[0], vb, pa0, pa1, pa2, pa3); pv_one<1>(o[1], vb, pa0, pa1, pa2, pa3); pv_one<2>(o[2], vb, pa0, pa1, pa2, pa3); pv_one<3>(o[3], vb, pa0, pa1, pa2, pa3);
; }
	s_nop 0
	v_mfma_f32_32x32x16_bf16 v[2:17], v[146:149], v[214:217], v[2:17]
	ds_read_b64_tr_b16 v[214:215], v151 offset:0x200
	ds_read_b64_tr_b16 v[216:217], v151 offset:0xa00
	s_waitcnt lgkmcnt(6)
	v_mfma_f32_32x32x16_bf16 v[2:17], v[210:213], v[218:221], v[2:17]
	ds_read_b64_tr_b16 v[218:219], v151 offset:0x1200
	ds_read_b64_tr_b16 v[220:221], v151 offset:0x1a00
	s_waitcnt lgkmcnt(6)
	v_mfma_f32_32x32x16_bf16 v[2:17], v[152:155], v[222:225], v[2:17]
	ds_read_b64_tr_b16 v[222:223], v151 offset:0x2200
	ds_read_b64_tr_b16 v[224:225], v151 offset:0x2a00
	s_waitcnt lgkmcnt(6)
	v_mfma_f32_32x32x16_bf16 v[2:17], v[156:159], v[226:229], v[2:17]
	ds_read_b64_tr_b16 v[226:227], v151 offset:0x3200
	ds_read_b64_tr_b16 v[228:229], v151 offset:0x3a00
	s_waitcnt lgkmcnt(6)
	v_mfma_f32_32x32x16_bf16 v[50:65], v[146:149], v[214:217], v[50:65]
	ds_read_b64_tr_b16 v[214:215], v151 offset:0x400
	ds_read_b64_tr_b16 v[216:217], v151 offset:0xc00
	s_waitcnt lgkmcnt(6)
	v_mfma_f32_32x32x16_bf16 v[50:65], v[210:213], v[218:221], v[50:65]
	ds_read_b64_tr_b16 v[218:219], v151 offset:0x1400
	ds_read_b64_tr_b16 v[220:221], v151 offset:0x1c00
	s_waitcnt lgkmcnt(6)
	v_mfma_f32_32x32x16_bf16 v[50:65], v[152:155], v[222:225], v[50:65]
	ds_read_b64_tr_b16 v[222:223], v151 offset:0x2400
	ds_read_b64_tr_b16 v[224:225], v151 offset:0x2c00
	s_waitcnt lgkmcnt(6)
	v_mfma_f32_32x32x16_bf16 v[50:65], v[156:159], v[226:229], v[50:65]
	ds_read_b64_tr_b16 v[226:227], v151 offset:0x3400
	ds_read_b64_tr_b16 v[228:229], v151 offset:0x3c00
	s_waitcnt lgkmcnt(6)
	v_mfma_f32_32x32x16_bf16 v[34:49], v[146:149], v[214:217], v[34:49]
	ds_read_b64_tr_b16 v[214:215], v151 offset:0x600
	ds_read_b64_tr_b16 v[216:217], v151 offset:0xe00
	s_waitcnt lgkmcnt(6)
	v_mfma_f32_32x32x16_bf16 v[34:49], v[210:213], v[218:221], v[34:49]
	ds_read_b64_tr_b16 v[218:219], v151 offset:0x1600
	ds_read_b64_tr_b16 v[220:221], v151 offset:0x1e00
	s_waitcnt lgkmcnt(6)
	v_mfma_f32_32x32x16_bf16 v[34:49], v[152:155], v[222:225], v[34:49]
	ds_read_b64_tr_b16 v[222:223], v151 offset:0x2600
	ds_read_b64_tr_b16 v[224:225], v151 offset:0x2e00
	s_waitcnt lgkmcnt(6)
	v_mfma_f32_32x32x16_bf16 v[34:49], v[156:159], v[226:229], v[34:49]
	ds_read_b64_tr_b16 v[226:227], v151 offset:0x3600
	ds_read_b64_tr_b16 v[228:229], v151 offset:0x3e00
	s_waitcnt lgkmcnt(6)
	v_mfma_f32_32x32x16_bf16 v[18:33], v[146:149], v[214:217], v[18:33]
	v_max_f32_e32 v146, v82, v83
	v_max3_f32 v146, v146, v84, v85
	v_max3_f32 v146, v146, v86, v87
	v_max3_f32 v146, v146, v88, v89
	v_max3_f32 v146, v146, v90, v91
	v_max3_f32 v146, v146, v92, v93
	v_max3_f32 v146, v146, v94, v95
	v_max3_f32 v146, v146, v96, v97
	v_max3_f32 v146, v146, v66, v67
	s_waitcnt lgkmcnt(4)
	v_mfma_f32_32x32x16_bf16 v[18:33], v[210:213], v[218:221], v[18:33]
	v_max3_f32 v146, v146, v68, v69
	v_max3_f32 v146, v146, v70, v71
	v_max3_f32 v146, v146, v72, v73
	v_max3_f32 v146, v146, v74, v75
	v_max3_f32 v146, v146, v76, v77
	v_max3_f32 v146, v146, v78, v79
	v_max3_f32 v146, v146, v80, v81
	v_mov_b32_e32 v147, v146
	s_waitcnt lgkmcnt(2)
	v_mfma_f32_32x32x16_bf16 v[18:33], v[152:155], v[222:225], v[18:33]
	s_nop 0
	v_permlane32_swap_b32_e32 v146, v147
	v_max_f32_e32 v146, v146, v147
	v_sub_f32_e32 v147, v146, v150
	v_cmp_ge_f32_e32 vcc, s25, v147
	v_max_f32_e32 v146, v150, v146
	v_sub_f32_e32 v147, v150, v146
	s_cmp_eq_u64 vcc, exec
	v_mul_f32_e32 v147, 0x3e0293ee, v147
	s_waitcnt lgkmcnt(0)
	v_mfma_f32_32x32x16_bf16 v[18:33], v[156:159], v[226:229], v[18:33]
	s_setprio 0
	s_cselect_b64 s[42:43], -1, 0
	v_exp_f32_e32 v147, v147
	s_add_i32 s7, s9, 0x4000
	s_cmp_lg_u32 s6, 2
	s_cselect_b32 s6, s7, 0
	s_add_i32 s10, s6, 0
	v_cndmask_b32_e64 v196, v147, 1.0, s[42:43]
	v_cmp_gt_f32_e32 vcc, 1.0, v196
	s_cbranch_vccz .LBB0_264
	s_and_saveexec_b64 s[6:7], s[38:39]
	ds_write_b32 v190, v196 offset:128
	s_or_b64 exec, exec, s[6:7]
	s_waitcnt lgkmcnt(0)
	v_add_u32_e32 v147, v173, v181
	ds_read_b128 v[152:155], v147 offset:224
	ds_read_b128 v[156:159], v147 offset:192
	ds_read_b128 v[210:213], v147 offset:160
	ds_read_b128 v[214:217], v147 offset:128
	s_waitcnt lgkmcnt(3)
	v_pk_mul_f32 v[14:15], v[14:15], v[152:153]
	s_waitcnt lgkmcnt(2)
	v_pk_mul_f32 v[10:11], v[10:11], v[156:157]
	s_waitcnt lgkmcnt(1)
	v_pk_mul_f32 v[6:7], v[6:7], v[210:211]
	v_pk_mul_f32 v[16:17], v[16:17], v[154:155]
	v_pk_mul_f32 v[12:13], v[12:13], v[158:159]
	v_pk_mul_f32 v[8:9], v[8:9], v[212:213]
	s_waitcnt lgkmcnt(0)
	v_pk_mul_f32 v[4:5], v[4:5], v[216:217]
	v_pk_mul_f32 v[2:3], v[2:3], v[214:215]
	v_pk_mul_f32 v[62:63], v[62:63], v[152:153]
	v_pk_mul_f32 v[58:59], v[58:59], v[156:157]
	v_pk_mul_f32 v[54:55], v[54:55], v[210:211]
	v_pk_mul_f32 v[64:65], v[64:65], v[154:155]
	v_pk_mul_f32 v[60:61], v[60:61], v[158:159]
	v_pk_mul_f32 v[56:57], v[56:57], v[212:213]
	v_pk_mul_f32 v[52:53], v[52:53], v[216:217]
	v_pk_mul_f32 v[50:51], v[50:51], v[214:215]
	v_pk_mul_f32 v[46:47], v[46:47], v[152:153]
	v_pk_mul_f32 v[42:43], v[42:43], v[156:157]
	v_pk_mul_f32 v[38:39], v[38:39], v[210:211]
	v_pk_mul_f32 v[48:49], v[48:49], v[154:155]
	v_pk_mul_f32 v[44:45], v[44:45], v[158:159]
	v_pk_mul_f32 v[40:41], v[40:41], v[212:213]
	v_pk_mul_f32 v[36:37], v[36:37], v[216:217]
	v_pk_mul_f32 v[34:35], v[34:35], v[214:215]
	v_pk_mul_f32 v[30:31], v[30:31], v[152:153]
	v_pk_mul_f32 v[26:27], v[26:27], v[156:157]
	v_pk_mul_f32 v[22:23], v[22:23], v[210:211]
	v_pk_mul_f32 v[32:33], v[32:33], v[154:155]
	v_pk_mul_f32 v[28:29], v[28:29], v[158:159]
	v_pk_mul_f32 v[24:25], v[24:25], v[212:213]
	v_pk_mul_f32 v[20:21], v[20:21], v[216:217]
	v_pk_mul_f32 v[18:19], v[18:19], v[214:215]

; #define SBAR() __builtin_amdgcn_sched_barrier(0)
; #define SLOAD(i, t) do { const long rb_ = TROW(t); const char* vt_ = (const char*)Vh + rb_ * (LDK * 2); const char* kt_ = (const char*)Kh + rb_ * (LDK * 2); \
;     sr_[i].vs0 = *(const bf16x8*)(vt_ + lo0); sr_[i].vs1 = *(const bf16x8*)(vt_ + lo0 + 32 * LDK * 2); \
;     sr_[i].ks0 = *(const bf16x8*)(kt_ + lo0); sr_[i].ks1 = *(const bf16x8*)(kt_ + lo0 + 32 * LDK * 2); } while (0)
; #define SWAIT() asm volatile("s_waitcnt vmcnt(0)" ::: "memory")
; #define RESC(a) do { if (__any((a) < 1.f)) { if (hi == 0) al_l[r32] = (a); asm volatile("s_waitcnt lgkmcnt(0)" ::: "memory"); \
;     _Pragma("unroll") for (int d = 0; d < 4; ++d) _Pragma("unroll") for (int r = 0; r < 16; ++r) o[d][r] *= al_l[crow(r, hi)]; } } while (0)
; template <int D0> __device__ __forceinline__ void pv_one(f32x16& od, int vb, bf16x8 pa0, bf16x8 pa1, bf16x8 pa2, bf16x8 pa3) {
;   const s16x4 l0 = tr_read<v_rd_off(D0, 0, 0)>(vb), h0 = tr_read<v_rd_off(D0, 0, 1)>(vb), l1 = tr_read<v_rd_off(D0, 1, 0)>(vb), h1 = tr_read<v_rd_off(D0, 1, 1)>(vb);
;   const s16x4 l2 = tr_read<v_rd_off(D0, 2, 0)>(vb), h2 = tr_read<v_rd_off(D0, 2, 1)>(vb), l3 = tr_read<v_rd_off(D0, 3, 0)>(vb), h3 = tr_read<v_rd_off(D0, 3, 1)>(vb);
;   asm volatile("s_waitcnt lgkmcnt(0)" ::: "memory"); SBAR();
;     ...
;   od = __builtin_amdgcn_mfma_f32_32x32x16_bf16(pa0, PK(l0, h0), od, 0, 0, 0);
;   od = __builtin_amdgcn_mfma_f32_32x32x16_bf16(pa1, PK(l1, h1), od, 0, 0, 0);
;   od = __builtin_amdgcn_mfma_f32_32x32x16_bf16(pa2, PK(l2, h2), od, 0, 0, 0);
;   od = __builtin_amdgcn_mfma_f32_32x32x16_bf16(pa3, PK(l3, h3), od, 0, 0, 0);
;     ...
; }
; __device__ __forceinline__ void pv_d0(f32x16* o, int vb, bf16x8 pa0, bf16x8 pa1, bf16x8 pa2, bf16x8 pa3) {
;   pv_one<0>(o[0], vb, pa0, pa1, pa2, pa3); pv_one<1>(o[1], vb, pa0, pa1, pa2, pa3); pv_one<2>(o[2], vb, pa0, pa1, pa2, pa3); pv_one<3>(o[3], vb, pa0, pa1, pa2, pa3);
; }
; template <bool META>
; __device__ __forceinline__ void attn_unit(const bf16_t* Q, bf16_t* Oo, const bf16_t* __restrict__ Kb, const bf16_t* __restrict__ Vb, int b, int kvh, int h, int qb, char* lds, const int tid, const float* qn, const float* RT) {
;     ...
;     if (j + 2 < NT) SLOAD(SE, j + 2);
;     SBAR();
;     pv_d0(o, vb0 + bc * (int)SHM_V, pa0, pa1, pa2, pa3); partialSM(pA0, pA1, m_reg, mnA, alA);
;     SWAIT(); SWRITE(bp, SO);
;     RESC(alA); __syncthreads();
.Latt_nomask:
	v_add_u32_e32 v198, s9, v178
	ds_read_b64_tr_b16 v[212:213], v198 offset:0
	ds_read_b64_tr_b16 v[214:215], v198 offset:0x800
	ds_read_b64_tr_b16 v[216:217], v198 offset:0x1000
	ds_read_b64_tr_b16 v[218:219], v198 offset:0x1800
	ds_read_b64_tr_b16 v[220:221], v198 offset:0x2000
	ds_read_b64_tr_b16 v[222:223], v198 offset:0x2800
	ds_read_b64_tr_b16 v[224:225], v198 offset:0x3000
	ds_read_b64_tr_b16 v[226:227], v198 offset:0x3800
	s_setprio 1
	s_andn2_b64 vcc, exec, s[0:1]
	s_cbranch_vccnz .LBB0_266
	s_add_u32 s0, s90, 64
	s_addc_u32 s1, s91, 0
	s_cmpk_lt_u32 s4, 0xfe
	s_cselect_b32 s1, s1, s44
	s_cselect_b32 s0, s0, s31
	s_lshl_b64 s[0:1], s[0:1], 9
	s_add_i32 s19, s8, s18
	s_add_u32 s16, s12, s0
	s_addc_u32 s17, s13, s1
	s_mov_b32 m0, s19
	s_nop 0
	global_load_lds_dwordx4 v187, s[16:17]
	s_add_i32 m0, s19, 0x380
	s_nop 0
	global_load_lds_dwordx4 v187, s[16:17] offset:128
	s_add_u32 s16, s14, s0
	s_addc_u32 s17, s15, s1
	s_add_i32 m0, s19, 0xc000
	s_nop 0
	global_load_lds_dwordx4 v188, s[16:17]
	s_add_u32 s16, s16, 0x4000
	s_addc_u32 s17, s17, 0
	s_add_i32 m0, s19, 0xc400
	s_nop 0
	global_load_lds_dwordx4 v188, s[16:17]
.LBB0_266:
	s_waitcnt lgkmcnt(6)
	s_nop 0
	v_mfma_f32_32x32x16_bf16 v[2:17], v[146:149], v[212:215], v[2:17]
	ds_read_b64_tr_b16 v[212:213], v198 offset:0x200
	ds_read_b64_tr_b16 v[214:215], v198 offset:0xa00
	s_waitcnt lgkmcnt(6)
	v_mfma_f32_32x32x16_bf16 v[2:17], v[150:153], v[216:219], v[2:17]
	ds_read_b64_tr_b16 v[216:217], v198 offset:0x1200
	ds_read_b64_tr_b16 v[218:219], v198 offset:0x1a00
	s_waitcnt lgkmcnt(6)
	v_mfma_f32_32x32x16_bf16 v[2:17], v[154:157], v[220:223], v[2:17]
	ds_read_b64_tr_b16 v[220:221], v198 offset:0x2200
	ds_read_b64_tr_b16 v[222:223], v198 offset:0x2a00
	s_waitcnt lgkmcnt(6)
	v_mfma_f32_32x32x16_bf16 v[2:17], v[158:161], v[224:227], v[2:17]
	ds_read_b64_tr_b16 v[224:225], v198 offset:0x3200
	ds_read_b64_tr_b16 v[226:227], v198 offset:0x3a00
	s_waitcnt lgkmcnt(6)
	v_mfma_f32_32x32x16_bf16 v[50:65], v[146:149], v[212:215], v[50:65]
	ds_read_b64_tr_b16 v[212:213], v198 offset:0x400
	ds_read_b64_tr_b16 v[214:215], v198 offset:0xc00
	s_waitcnt lgkmcnt(6)
	v_mfma_f32_32x32x16_bf16 v[50:65], v[150:153], v[216:219], v[50:65]
	ds_read_b64_tr_b16 v[216:217], v198 offset:0x1400
	ds_read_b64_tr_b16 v[218:219], v198 offset:0x1c00
	s_waitcnt lgkmcnt(6)
	v_mfma_f32_32x32x16_bf16 v[50:65], v[154:157], v[220:223], v[50:65]
	ds_read_b64_tr_b16 v[220:221], v198 offset:0x2400
	ds_read_b64_tr_b16 v[222:223], v198 offset:0x2c00
	s_waitcnt lgkmcnt(6)
	v_mfma_f32_32x32x16_bf16 v[50:65], v[158:161], v[224:227], v[50:65]
	ds_read_b64_tr_b16 v[224:225], v198 offset:0x3400
	ds_read_b64_tr_b16 v[226:227], v198 offset:0x3c00
	s_waitcnt lgkmcnt(6)
	v_mfma_f32_32x32x16_bf16 v[34:49], v[146:149], v[212:215], v[34:49]
	ds_read_b64_tr_b16 v[212:213], v198 offset:0x600
	ds_read_b64_tr_b16 v[214:215], v198 offset:0xe00
	s_waitcnt lgkmcnt(6)
	v_mfma_f32_32x32x16_bf16 v[34:49], v[150:153], v[216:219], v[34:49]
	ds_read_b64_tr_b16 v[216:217], v198 offset:0x1600
	ds_read_b64_tr_b16 v[218:219], v198 offset:0x1e00
	s_waitcnt lgkmcnt(6)
	v_mfma_f32_32x32x16_bf16 v[34:49], v[154:157], v[220:223], v[34:49]
	ds_read_b64_tr_b16 v[220:221], v198 offset:0x2600
	ds_read_b64_tr_b16 v[222:223], v198 offset:0x2e00
	s_waitcnt lgkmcnt(6)
	v_mfma_f32_32x32x16_bf16 v[34:49], v[158:161], v[224:227], v[34:49]
	ds_read_b64_tr_b16 v[224:225], v198 offset:0x3600
	ds_read_b64_tr_b16 v[226:227], v198 offset:0x3e00
	s_waitcnt lgkmcnt(6)
	v_mfma_f32_32x32x16_bf16 v[18:33], v[146:149], v[212:215], v[18:33]
	v_max_f32_e32 v230, v66, v67
	v_max3_f32 v230, v230, v68, v69
	v_max3_f32 v230, v230, v70, v71
	v_max3_f32 v230, v230, v72, v73
	v_max3_f32 v230, v230, v74, v75
	v_max3_f32 v230, v230, v76, v77
	v_max3_f32 v230, v230, v78, v79
	s_waitcnt lgkmcnt(4)
	v_mfma_f32_32x32x16_bf16 v[18:33], v[150:153], v[216:219], v[18:33]
	v_max3_f32 v230, v230, v80, v81
	v_max3_f32 v230, v230, v82, v83
	v_max3_f32 v230, v230, v84, v85
	v_max3_f32 v230, v230, v86, v87
	v_max3_f32 v230, v230, v88, v89
	v_max3_f32 v230, v230, v90, v91
	v_max3_f32 v230, v230, v92, v93
	v_max3_f32 v230, v230, v94, v95
	s_waitcnt lgkmcnt(2)
	v_mfma_f32_32x32x16_bf16 v[18:33], v[154:157], v[220:223], v[18:33]
	v_max3_f32 v230, v230, v96, v97
	v_mov_b32_e32 v231, v230
	s_nop 1
	v_permlane32_swap_b32_e32 v230, v231
	v_max_f32_e32 v230, v230, v231
	v_sub_f32_e32 v231, v230, v209
	v_cmp_ge_f32_e32 vcc, s25, v231
	v_max_f32_e32 v231, v209, v230
	s_waitcnt lgkmcnt(0)
	v_mfma_f32_32x32x16_bf16 v[18:33], v[158:161], v[224:227], v[18:33]
	s_setprio 0
	v_sub_f32_e32 v230, v209, v231
	v_mul_f32_e32 v230, 0x3e0293ee, v230
	s_cmp_eq_u64 vcc, exec
	v_exp_f32_e32 v230, v230
	s_cselect_b64 s[40:41], -1, 0
	s_add_i32 s0, s8, 0
	v_cndmask_b32_e64 v230, v230, 1.0, s[40:41]
	v_cmp_gt_f32_e32 vcc, 1.0, v230
	s_cbranch_vccz .LBB0_270
	s_and_saveexec_b64 s[0:1], s[38:39]
	ds_write_b32 v190, v230 offset:128
	s_or_b64 exec, exec, s[0:1]
	s_waitcnt lgkmcnt(0)
	v_add_u32_e32 v236, v173, v181
	ds_read_b128 v[232:235], v236 offset:224
	ds_read_b128 v[130:133], v236 offset:192
	ds_read_b128 v[134:137], v236 offset:160
	ds_read_b128 v[138:141], v236 offset:128
	s_waitcnt lgkmcnt(3)
	v_pk_mul_f32 v[14:15], v[14:15], v[232:233]
	s_waitcnt lgkmcnt(2)
	v_pk_mul_f32 v[10:11], v[10:11], v[130:131]
	s_waitcnt lgkmcnt(1)
	v_pk_mul_f32 v[6:7], v[6:7], v[134:135]
	v_pk_mul_f32 v[16:17], v[16:17], v[234:235]
	v_pk_mul_f32 v[12:13], v[12:13], v[132:133]
	v_pk_mul_f32 v[8:9], v[8:9], v[136:137]
	s_waitcnt lgkmcnt(0)
	v_pk_mul_f32 v[4:5], v[4:5], v[140:141]
	v_pk_mul_f32 v[2:3], v[2:3], v[138:139]
	v_pk_mul_f32 v[62:63], v[62:63], v[232:233]
	v_pk_mul_f32 v[58:59], v[58:59], v[130:131]
	v_pk_mul_f32 v[54:55], v[54:55], v[134:135]
	v_pk_mul_f32 v[64:65], v[64:65], v[234:235]
	v_pk_mul_f32 v[60:61], v[60:61], v[132:133]
	v_pk_mul_f32 v[56:57], v[56:57], v[136:137]
	v_pk_mul_f32 v[52:53], v[52:53], v[140:141]
	v_pk_mul_f32 v[50:51], v[50:51], v[138:139]
	v_pk_mul_f32 v[46:47], v[46:47], v[232:233]
	v_pk_mul_f32 v[42:43], v[42:43], v[130:131]
	v_pk_mul_f32 v[38:39], v[38:39], v[134:135]
	v_pk_mul_f32 v[48:49], v[48:49], v[234:235]
	v_pk_mul_f32 v[44:45], v[44:45], v[132:133]
	v_pk_mul_f32 v[40:41], v[40:41], v[136:137]
	v_pk_mul_f32 v[36:37], v[36:37], v[140:141]
	v_pk_mul_f32 v[34:35], v[34:35], v[138:139]
	v_pk_mul_f32 v[30:31], v[30:31], v[232:233]
	v_pk_mul_f32 v[26:27], v[26:27], v[130:131]
	v_pk_mul_f32 v[22:23], v[22:23], v[134:135]
	v_pk_mul_f32 v[32:33], v[32:33], v[234:235]
	v_pk_mul_f32 v[28:29], v[28:29], v[132:133]
	v_pk_mul_f32 v[24:25], v[24:25], v[136:137]
	v_pk_mul_f32 v[20:21], v[20:21], v[140:141]
	v_pk_mul_f32 v[18:19], v[18:19], v[138:139]
